# v18: v16 plus the -inf guard on the running max (cmp + cndmask) replaced by one v_max against -1e30 in the six attention bodies (shorter serial chain before the exp block)
# baseline (speedup 1.0000x reference)
; __device__ __forceinline__ float half_max(float v) { float a, b; half_pair(v, a, b); return fmaxf(a, b); }
; __device__ __forceinline__ void att_softmax(f32x16& s, float sc, float& m, float& l, f32x16 (&o)[4], bf16x8& pf0, bf16x8& pf1) {
;     float mx = fmaxf(fmaxf(s[0], s[1]), fmaxf(s[2], s[3]));
; #pragma unroll
;     for (int i = 4; i < 16; i += 4) mx = fmaxf(mx, fmaxf(fmaxf(s[i], s[i + 1]), fmaxf(s[i + 2], s[i + 3])));
;     mx = half_max(mx);
;     const float mnew = fmaxf(m, mx * sc);
;     const float msafe = (mnew == -INFINITY) ? 0.f : mnew;
;     const float alpha = __builtin_amdgcn_exp2f(m - msafe);
.LBB0_116:
	s_nop 9
	v_max_f32_e32 v200, v67, v67
	v_max_f32_e32 v201, v66, v66
	v_max_f32_e32 v200, v201, v200
	v_max_f32_e32 v201, v69, v69
	v_max_f32_e32 v202, v68, v68
	v_max_f32_e32 v201, v202, v201
	v_max_f32_e32 v202, v73, v73
	v_max_f32_e32 v203, v72, v72
	v_max_f32_e32 v202, v203, v202
	v_max3_f32 v202, v70, v71, v202
	v_max3_f32 v200, v200, v201, v202
	v_max_f32_e32 v201, v77, v77
	v_max_f32_e32 v202, v76, v76
	v_max_f32_e32 v201, v202, v201
	v_max_f32_e32 v202, v81, v81
	v_max_f32_e32 v203, v80, v80
	v_max_f32_e32 v202, v203, v202
	v_max3_f32 v201, v74, v75, v201
	v_max3_f32 v202, v78, v79, v202
	v_max3_f32 v200, v200, v201, v202
	v_mov_b32_e32 v201, v200
	s_nop 1
	v_permlane32_swap_b32_e32 v200, v201
	v_max_f32_e32 v201, v201, v201
	v_max_f32_e32 v200, v200, v200
	v_max_f32_e32 v200, v200, v201
	v_mul_f32_e32 v200, 0x3dd53b94, v200
	v_max_f32_e32 v201, v232, v232
	v_max_f32_e32 v238, v201, v200
	v_max_f32_e32 v234, 0xf149f2ca, v238
	v_sub_f32_e32 v200, v232, v234
	v_exp_f32_e32 v224, v200

; __device__ __forceinline__ float half_max(float v) { float a, b; half_pair(v, a, b); return fmaxf(a, b); }
; __device__ __forceinline__ void att_softmax(f32x16& s, float sc, float& m, float& l, f32x16 (&o)[4], bf16x8& pf0, bf16x8& pf1) {
;     float mx = fmaxf(fmaxf(s[0], s[1]), fmaxf(s[2], s[3]));
; #pragma unroll
;     for (int i = 4; i < 16; i += 4) mx = fmaxf(mx, fmaxf(fmaxf(s[i], s[i + 1]), fmaxf(s[i + 2], s[i + 3])));
;     mx = half_max(mx);
;     const float mnew = fmaxf(m, mx * sc);
;     const float msafe = (mnew == -INFINITY) ? 0.f : mnew;
;     const float alpha = __builtin_amdgcn_exp2f(m - msafe);
.LBB0_123:
	s_nop 9
	v_max_f32_e32 v200, v67, v67
	v_max_f32_e32 v201, v66, v66
	v_max_f32_e32 v200, v201, v200
	v_max_f32_e32 v201, v69, v69
	v_max_f32_e32 v202, v68, v68
	v_max_f32_e32 v201, v202, v201
	v_max_f32_e32 v202, v73, v73
	v_max_f32_e32 v203, v72, v72
	v_max_f32_e32 v202, v203, v202
	v_max3_f32 v202, v70, v71, v202
	v_max3_f32 v200, v200, v201, v202
	v_max_f32_e32 v201, v77, v77
	v_max_f32_e32 v202, v76, v76
	v_max_f32_e32 v201, v202, v201
	v_max_f32_e32 v202, v81, v81
	v_max_f32_e32 v203, v80, v80
	v_max_f32_e32 v202, v203, v202
	v_max3_f32 v201, v74, v75, v201
	v_max3_f32 v202, v78, v79, v202
	v_max3_f32 v200, v200, v201, v202
	v_mov_b32_e32 v201, v200
	s_nop 1
	v_permlane32_swap_b32_e32 v200, v201
	v_max_f32_e32 v201, v201, v201
	v_max_f32_e32 v200, v200, v200
	v_max_f32_e32 v200, v200, v201
	v_mul_f32_e32 v200, 0x3dd53b94, v200
	v_max_f32_e32 v201, v238, v238
	v_max_f32_e32 v232, v201, v200
	v_max_f32_e32 v233, 0xf149f2ca, v232
	v_sub_f32_e32 v200, v238, v233
	v_exp_f32_e32 v224, v200

; __device__ __forceinline__ float half_max(float v) { float a, b; half_pair(v, a, b); return fmaxf(a, b); }
;     __device__ __forceinline__ bool need(int kv0) const { return (kv0 + 31 >= qw - window) && (kv0 <= qw + 31); }
; __device__ __forceinline__ void att_softmax(f32x16& s, float sc, float& m, float& l, f32x16 (&o)[4], bf16x8& pf0, bf16x8& pf1) {
;     float mx = fmaxf(fmaxf(s[0], s[1]), fmaxf(s[2], s[3]));
; #pragma unroll
;     for (int i = 4; i < 16; i += 4) mx = fmaxf(mx, fmaxf(fmaxf(s[i], s[i + 1]), fmaxf(s[i + 2], s[i + 3])));
;     mx = half_max(mx);
;     const float mnew = fmaxf(m, mx * sc);
;     const float msafe = (mnew == -INFINITY) ? 0.f : mnew;
;     const float alpha = __builtin_amdgcn_exp2f(m - msafe);
.LBB0_144:
	s_lshr_b32 s62, s88, 8
	s_cmp_eq_u32 s62, s50
	s_cselect_b64 s[60:61], -1, 0
	s_lshl_b32 s62, 1, s62
	v_and_b32_e32 v200, s62, v183
	v_cmp_ne_u32_e32 vcc, 0, v200
	s_or_b64 vcc, s[60:61], vcc
	s_nop 2
	v_cndmask_b32_e32 v245, v241, v66, vcc
	v_cndmask_b32_e32 v240, v241, v67, vcc
	v_cndmask_b32_e32 v238, v241, v68, vcc
	v_cndmask_b32_e32 v235, v241, v69, vcc
	v_max_f32_e32 v66, v240, v240
	v_max_f32_e32 v67, v245, v245
	v_cndmask_b32_e32 v232, v241, v72, vcc
	v_cndmask_b32_e32 v231, v241, v73, vcc
	v_cndmask_b32_e32 v230, v241, v74, vcc
	v_cndmask_b32_e32 v74, v241, v75, vcc
	v_max_f32_e32 v66, v67, v66
	v_max_f32_e32 v67, v235, v235
	v_max_f32_e32 v75, v238, v238
	v_cndmask_b32_e32 v73, v241, v76, vcc
	v_max_f32_e32 v67, v75, v67
	v_max_f32_e32 v75, v231, v231
	v_max_f32_e32 v76, v232, v232
	v_cndmask_b32_e32 v234, v241, v70, vcc
	v_cndmask_b32_e32 v233, v241, v71, vcc
	v_max_f32_e32 v75, v76, v75
	v_cndmask_b32_e32 v72, v241, v77, vcc
	v_max3_f32 v75, v234, v233, v75
	v_cndmask_b32_e32 v69, v241, v80, vcc
	v_cndmask_b32_e32 v68, v241, v81, vcc
	v_max3_f32 v66, v66, v67, v75
	v_max_f32_e32 v67, v72, v72
	v_max_f32_e32 v75, v73, v73
	v_max_f32_e32 v67, v75, v67
	v_max_f32_e32 v75, v68, v68
	v_max_f32_e32 v76, v69, v69
	v_cndmask_b32_e32 v71, v241, v78, vcc
	v_cndmask_b32_e32 v70, v241, v79, vcc
	v_max_f32_e32 v75, v76, v75
	v_max3_f32 v67, v230, v74, v67
	v_max3_f32 v75, v71, v70, v75
	v_max3_f32 v66, v66, v67, v75
	v_mov_b32_e32 v67, v66
	s_nop 1
	v_permlane32_swap_b32_e32 v66, v67
	v_max_f32_e32 v67, v67, v67
	v_max_f32_e32 v66, v66, v66
	v_max_f32_e32 v66, v66, v67
	v_mul_f32_e32 v66, 0x3e0293ee, v66
	v_max_f32_e32 v67, v181, v181
	v_max_f32_e32 v67, v67, v66
	v_max_f32_e32 v75, 0xf149f2ca, v67
	v_sub_f32_e32 v66, v181, v75
	v_exp_f32_e32 v66, v66

; __device__ __forceinline__ float half_max(float v) { float a, b; half_pair(v, a, b); return fmaxf(a, b); }
; __device__ __forceinline__ void att_softmax(f32x16& s, float sc, float& m, float& l, f32x16 (&o)[4], bf16x8& pf0, bf16x8& pf1) {
;     float mx = fmaxf(fmaxf(s[0], s[1]), fmaxf(s[2], s[3]));
; #pragma unroll
;     for (int i = 4; i < 16; i += 4) mx = fmaxf(mx, fmaxf(fmaxf(s[i], s[i + 1]), fmaxf(s[i + 2], s[i + 3])));
;     mx = half_max(mx);
;     const float mnew = fmaxf(m, mx * sc);
;     const float msafe = (mnew == -INFINITY) ? 0.f : mnew;
;     const float alpha = __builtin_amdgcn_exp2f(m - msafe);
.LBB0_276:
	s_nop 9
	v_max3_f32 v0, v80, v81, v82
	v_max3_f32 v136, v83, v84, v85
	v_max3_f32 v137, v86, v87, v88
	v_max3_f32 v0, v0, v136, v137
	v_max3_f32 v136, v89, v90, v91
	v_max3_f32 v137, v92, v93, v94
	v_max3_f32 v136, v136, v137, v95
	v_max_f32_e32 v0, v0, v136
	v_mov_b32_e32 v136, v0
	s_nop 1
	v_permlane32_swap_b32_e32 v0, v136
	v_max_f32_e32 v0, v0, v136
	v_mul_f32_e32 v0, 0x3e38aa3b, v0
	v_max_f32_e32 v221, v240, v0
	v_max_f32_e32 v181, 0xf149f2ca, v221
	v_sub_f32_e32 v0, v240, v181
	v_exp_f32_e32 v0, v0

; __device__ __forceinline__ float half_max(float v) { float a, b; half_pair(v, a, b); return fmaxf(a, b); }
; __device__ __forceinline__ void att_softmax(f32x16& s, float sc, float& m, float& l, f32x16 (&o)[4], bf16x8& pf0, bf16x8& pf1) {
;     float mx = fmaxf(fmaxf(s[0], s[1]), fmaxf(s[2], s[3]));
; #pragma unroll
;     for (int i = 4; i < 16; i += 4) mx = fmaxf(mx, fmaxf(fmaxf(s[i], s[i + 1]), fmaxf(s[i + 2], s[i + 3])));
;     mx = half_max(mx);
;     const float mnew = fmaxf(m, mx * sc);
;     const float msafe = (mnew == -INFINITY) ? 0.f : mnew;
;     const float alpha = __builtin_amdgcn_exp2f(m - msafe);
.LBB0_302:
	v_add_u32_e32 v0, 27, v14
	v_alignbit_b32 v0, v0, v0, s100
	v_cmp_ge_u32_e64 s[8:9], s101, v0
	v_add_u32_e32 v0, 26, v14
	v_alignbit_b32 v0, v0, v0, s100
	v_cmp_ge_u32_e64 s[10:11], s101, v0
	s_nop 4
	v_cndmask_b32_e64 v80, v241, v80, s[8:9]
	v_add_u32_e32 v0, 25, v14
	v_alignbit_b32 v0, v0, v0, s100
	v_cmp_ge_u32_e64 s[8:9], s101, v0
	v_cndmask_b32_e64 v81, v241, v81, s[10:11]
	v_add_u32_e32 v0, 24, v14
	v_alignbit_b32 v0, v0, v0, s100
	v_cmp_ge_u32_e64 s[10:11], s101, v0
	v_cndmask_b32_e64 v82, v241, v82, s[8:9]
	v_add_u32_e32 v0, 19, v14
	v_alignbit_b32 v0, v0, v0, s100
	v_cmp_ge_u32_e64 s[8:9], s101, v0
	v_cndmask_b32_e64 v83, v241, v83, s[10:11]
	v_add_u32_e32 v0, 18, v14
	v_alignbit_b32 v0, v0, v0, s100
	v_cmp_ge_u32_e64 s[10:11], s101, v0
	v_cndmask_b32_e64 v84, v241, v84, s[8:9]
	v_add_u32_e32 v0, 17, v14
	v_alignbit_b32 v0, v0, v0, s100
	v_cmp_ge_u32_e64 s[8:9], s101, v0
	v_cndmask_b32_e64 v85, v241, v85, s[10:11]
	v_add_u32_e32 v0, 16, v14
	v_alignbit_b32 v0, v0, v0, s100
	v_cmp_ge_u32_e64 s[10:11], s101, v0
	v_cndmask_b32_e64 v86, v241, v86, s[8:9]
	v_add_u32_e32 v0, 11, v14
	v_alignbit_b32 v0, v0, v0, s100
	v_cmp_ge_u32_e64 s[8:9], s101, v0
	v_cndmask_b32_e64 v87, v241, v87, s[10:11]
	v_add_u32_e32 v0, 10, v14
	v_alignbit_b32 v0, v0, v0, s100
	v_cmp_ge_u32_e64 s[10:11], s101, v0
	v_cndmask_b32_e64 v88, v241, v88, s[8:9]
	v_add_u32_e32 v0, 9, v14
	v_alignbit_b32 v0, v0, v0, s100
	v_cmp_ge_u32_e64 s[8:9], s101, v0
	v_cndmask_b32_e64 v89, v241, v89, s[10:11]
	v_add_u32_e32 v0, 8, v14
	v_alignbit_b32 v0, v0, v0, s100
	v_cmp_ge_u32_e64 s[10:11], s101, v0
	v_cndmask_b32_e64 v90, v241, v90, s[8:9]
	v_add_u32_e32 v0, 3, v14
	v_alignbit_b32 v0, v0, v0, s100
	v_cmp_ge_u32_e64 s[8:9], s101, v0
	v_cndmask_b32_e64 v91, v241, v91, s[10:11]
	v_add_u32_e32 v0, 2, v14
	v_alignbit_b32 v0, v0, v0, s100
	v_cmp_ge_u32_e64 s[10:11], s101, v0
	v_cndmask_b32_e64 v92, v241, v92, s[8:9]
	v_add_u32_e32 v0, 1, v14
	v_alignbit_b32 v0, v0, v0, s100
	v_cmp_ge_u32_e64 s[8:9], s101, v0
	v_cndmask_b32_e64 v93, v241, v93, s[10:11]
	v_alignbit_b32 v0, v14, v14, s100
	v_cmp_ge_u32_e64 s[10:11], s101, v0
	v_cndmask_b32_e64 v94, v241, v94, s[8:9]
	v_max3_f32 v0, v80, v81, v82
	v_cndmask_b32_e64 v95, v241, v95, s[10:11]
	v_max3_f32 v200, v83, v84, v85
	v_max3_f32 v201, v86, v87, v88
	v_max3_f32 v0, v0, v200, v201
	v_max3_f32 v200, v89, v90, v91
	v_max3_f32 v201, v92, v93, v94
	v_max3_f32 v200, v200, v201, v95
	v_max_f32_e32 v0, v0, v200
	v_mov_b32_e32 v200, v0
	s_nop 1
	v_permlane32_swap_b32_e32 v0, v200
	v_max_f32_e32 v0, v0, v200
	v_mul_f32_e32 v0, 0x3e0293ee, v0
	v_max_f32_e32 v251, v247, v0
	v_max_f32_e32 v240, 0xf149f2ca, v251
	v_sub_f32_e32 v0, v247, v240
	v_exp_f32_e32 v0, v0

; #define LAS __attribute__((address_space(3)))
; __device__ __forceinline__ float half_max(float v) { float a, b; half_pair(v, a, b); return fmaxf(a, b); }
; #define MFMA32(a, b, c) __builtin_amdgcn_mfma_f32_32x32x16_bf16((a), (b), (c), 0, 0, 0)
; __device__ __forceinline__ void att_softmax(f32x16& s, float sc, float& m, float& l, f32x16 (&o)[4], bf16x8& pf0, bf16x8& pf1) {
;     float mx = fmaxf(fmaxf(s[0], s[1]), fmaxf(s[2], s[3]));
; #pragma unroll
;     for (int i = 4; i < 16; i += 4) mx = fmaxf(mx, fmaxf(fmaxf(s[i], s[i + 1]), fmaxf(s[i + 2], s[i + 3])));
;     mx = half_max(mx);
;     const float mnew = fmaxf(m, mx * sc);
;     const float msafe = (mnew == -INFINITY) ? 0.f : mnew;
;     const float alpha = __builtin_amdgcn_exp2f(m - msafe);
; template <int NC1, int NC2, class Ctl> ...
;     ...
;                 if (!KPRE && sb == 1 && nA) {
; #pragma unroll
;                     for (int c = 0; c < NC; ++c) kf[c] = *(const LAS bf16x8*)(kbase + 32 * Gm::KSTRIDE + c * 32); }
;                 f32x16 s;
; #pragma unroll
;                 for (int i = 0; i < 16; ++i) s[i] = 0.f;
; #pragma unroll
;                 for (int c = 0; c < NC; ++c) s = MFMA32(kf[c], qf[c], s);
.LBB0_311:
	s_waitcnt lgkmcnt(7)
	v_mfma_f32_32x32x16_bf16 v[80:95], v[140:143], v[2:5], 0
	s_waitcnt lgkmcnt(6)
	v_mfma_f32_32x32x16_bf16 v[80:95], v[144:147], v[6:9], v[80:95]
	s_waitcnt lgkmcnt(5)
	v_mfma_f32_32x32x16_bf16 v[80:95], v[148:151], v[10:13], v[80:95]
	s_waitcnt lgkmcnt(4)
	v_mfma_f32_32x32x16_bf16 v[80:95], v[152:155], v[96:99], v[80:95]
	s_waitcnt lgkmcnt(3)
	v_mfma_f32_32x32x16_bf16 v[80:95], v[156:159], v[100:103], v[80:95]
	ds_read2_b64 v[156:159], v250 offset0:136 offset1:138
	s_waitcnt lgkmcnt(3)
	v_mfma_f32_32x32x16_bf16 v[80:95], v[160:163], v[108:111], v[80:95]
	s_waitcnt lgkmcnt(2)
	v_mfma_f32_32x32x16_bf16 v[80:95], v[136:139], v[112:115], v[80:95]
	ds_read2_b64 v[140:143], v250 offset0:140 offset1:142
	ds_read2_b64 v[164:167], v15 offset0:168 offset1:170
	ds_read2_b64 v[160:163], v248 offset0:200 offset1:202
	ds_read2_b64 v[152:155], v249 offset0:232 offset1:234
	ds_read2_b64 v[148:151], v15 offset0:172 offset1:174
	ds_read2_b64 v[144:147], v248 offset0:204 offset1:206
	ds_read2_b64 v[136:139], v249 offset0:236 offset1:238
	s_waitcnt lgkmcnt(8)
	v_mfma_f32_32x32x16_bf16 v[80:95], v[132:135], v[120:123], v[80:95]
	v_add_u32_e32 v0, -5, v14
	v_alignbit_b32 v0, v0, v0, s100
	v_cmp_ge_u32_e64 s[6:7], s101, v0
	v_add_u32_e32 v0, -6, v14
	v_alignbit_b32 v0, v0, v0, s100
	v_cmp_ge_u32_e64 s[8:9], s101, v0
	s_nop 5
	v_cndmask_b32_e64 v15, v241, v80, s[6:7]
	v_add_u32_e32 v0, -7, v14
	v_alignbit_b32 v0, v0, v0, s100
	v_cmp_ge_u32_e64 s[6:7], s101, v0
	v_cndmask_b32_e64 v80, v241, v81, s[8:9]
	v_add_u32_e32 v0, -8, v14
	v_alignbit_b32 v0, v0, v0, s100
	v_cmp_ge_u32_e64 s[8:9], s101, v0
	v_cndmask_b32_e64 v81, v241, v82, s[6:7]
	v_add_u32_e32 v0, -13, v14
	v_alignbit_b32 v0, v0, v0, s100
	v_cmp_ge_u32_e64 s[6:7], s101, v0
	v_cndmask_b32_e64 v82, v241, v83, s[8:9]
	v_add_u32_e32 v0, -14, v14
	v_alignbit_b32 v0, v0, v0, s100
	v_cmp_ge_u32_e64 s[8:9], s101, v0
	v_cndmask_b32_e64 v83, v241, v84, s[6:7]
	v_add_u32_e32 v0, -15, v14
	v_alignbit_b32 v0, v0, v0, s100
	v_cmp_ge_u32_e64 s[6:7], s101, v0
	v_cndmask_b32_e64 v84, v241, v85, s[8:9]
	v_add_u32_e32 v0, -16, v14
	v_alignbit_b32 v0, v0, v0, s100
	v_cmp_ge_u32_e64 s[8:9], s101, v0
	v_cndmask_b32_e64 v85, v241, v86, s[6:7]
	v_subrev_u32_e32 v0, 21, v14
	v_alignbit_b32 v0, v0, v0, s100
	v_cmp_ge_u32_e64 s[6:7], s101, v0
	v_cndmask_b32_e64 v86, v241, v87, s[8:9]
	v_subrev_u32_e32 v0, 22, v14
	v_alignbit_b32 v0, v0, v0, s100
	v_cmp_ge_u32_e64 s[8:9], s101, v0
	v_cndmask_b32_e64 v87, v241, v88, s[6:7]
	v_subrev_u32_e32 v0, 23, v14
	v_alignbit_b32 v0, v0, v0, s100
	v_cmp_ge_u32_e64 s[6:7], s101, v0
	v_cndmask_b32_e64 v88, v241, v89, s[8:9]
	v_subrev_u32_e32 v0, 24, v14
	v_alignbit_b32 v0, v0, v0, s100
	v_cmp_ge_u32_e64 s[8:9], s101, v0
	v_cndmask_b32_e64 v89, v241, v90, s[6:7]
	v_subrev_u32_e32 v0, 29, v14
	v_alignbit_b32 v0, v0, v0, s100
	v_cmp_ge_u32_e64 s[6:7], s101, v0
	v_cndmask_b32_e64 v90, v241, v91, s[8:9]
	v_subrev_u32_e32 v0, 30, v14
	v_alignbit_b32 v0, v0, v0, s100
	v_cmp_ge_u32_e64 s[8:9], s101, v0
	v_cndmask_b32_e64 v91, v241, v92, s[6:7]
	v_subrev_u32_e32 v0, 31, v14
	v_alignbit_b32 v0, v0, v0, s100
	v_cmp_ge_u32_e64 s[6:7], s101, v0
	v_cndmask_b32_e64 v92, v241, v93, s[8:9]
	v_subrev_u32_e32 v0, 32, v14
	v_alignbit_b32 v0, v0, v0, s100
	v_cmp_ge_u32_e64 s[8:9], s101, v0
	v_cndmask_b32_e64 v93, v241, v94, s[6:7]
	v_max3_f32 v0, v15, v80, v81
	v_cndmask_b32_e64 v94, v241, v95, s[8:9]
	v_max3_f32 v95, v82, v83, v84
	v_max3_f32 v132, v85, v86, v87
	v_max3_f32 v0, v0, v95, v132
	v_max3_f32 v95, v88, v89, v90
	v_max3_f32 v132, v91, v92, v93
	v_max3_f32 v95, v95, v132, v94
	v_max_f32_e32 v0, v0, v95
	v_mov_b32_e32 v95, v0
	s_nop 1
	v_permlane32_swap_b32_e32 v0, v95
	v_max_f32_e32 v0, v0, v95
	v_mul_f32_e32 v0, 0x3e0293ee, v0
	v_max_f32_e32 v247, v251, v0
	v_max_f32_e32 v95, 0xf149f2ca, v247
	v_sub_f32_e32 v0, v251, v95
	v_exp_f32_e32 v0, v0
